# attention: odd hardware wave slots start the item 1792 cycles late (was 1280)
# baseline (speedup 1.0000x reference)
.LBB0_344:
	s_getreg_b32 s98, hwreg(HW_REG_HW_ID, 0, 4)
	s_bitcmp1_b32 s98, 0
	s_cbranch_scc0 .Lattn_nosleep
	s_sleep 28
	s_setprio 1
